# final output stores of the P8 epilogue written through (sc1 instead of nt): no dirty output lines left for the end-of-kernel L2 write-back
# speedup vs baseline: 1.0101x; 1.0101x over previous
.LBB0_1092:
	v_lshl_or_b32 v128, s47, 8, v166
	v_lshl_add_u32 v160, s46, 8, v164
	s_ashr_i32 s20, s46, 3
	v_ashrrev_i32_e32 v129, 31, v128
	v_ashrrev_i32_e32 v161, 31, v160
	s_mul_hi_i32 s21, s20, 0xc000
	s_mul_i32 s20, s20, 0xc000
	v_lshl_add_u64 v[158:159], v[128:129], 1, s[28:29]
	v_lshlrev_b64 v[130:131], 12, v[160:161]
	s_add_u32 s20, s35, s20
	v_lshl_add_u64 v[130:131], v[158:159], 0, v[130:131]
	v_lshlrev_b64 v[156:157], 2, v[128:129]
	s_addc_u32 s21, s44, s21
	global_load_dwordx2 v[170:171], v[130:131], off nt
	global_load_dwordx2 v[172:173], v[130:131], off offset:32 nt
	global_load_dwordx2 v[176:177], v[130:131], off offset:288 nt
	v_lshl_add_u64 v[128:129], s[20:21], 0, v[156:157]
	v_or_b32_e32 v178, 16, v160
	global_load_dwordx2 v[174:175], v[130:131], off offset:256 nt
	global_load_dwordx4 v[132:135], v[128:129], off offset:512
	global_load_dwordx4 v[140:143], v[128:129], off
	global_load_dwordx4 v[136:139], v[128:129], off offset:64
	v_ashrrev_i32_e32 v179, 31, v178
	global_load_dwordx4 v[128:131], v[128:129], off offset:576
	v_lshlrev_b64 v[162:163], 12, v[178:179]
	v_lshl_add_u64 v[162:163], v[158:159], 0, v[162:163]
	global_load_dwordx2 v[180:181], v[162:163], off nt
	global_load_dwordx2 v[182:183], v[162:163], off offset:32 nt
	global_load_dwordx2 v[184:185], v[162:163], off offset:256 nt
	global_load_dwordx2 v[186:187], v[162:163], off offset:288 nt
	v_or_b32_e32 v188, 32, v160
	v_ashrrev_i32_e32 v189, 31, v188
	v_lshlrev_b64 v[162:163], 12, v[188:189]
	v_lshl_add_u64 v[190:191], v[158:159], 0, v[162:163]
	global_load_dwordx2 v[192:193], v[190:191], off nt
	global_load_dwordx2 v[196:197], v[190:191], off offset:32 nt
	v_or_b32_e32 v162, 48, v160
	v_ashrrev_i32_e32 v163, 31, v162
	v_lshlrev_b64 v[198:199], 12, v[162:163]
	v_lshl_add_u64 v[198:199], v[158:159], 0, v[198:199]
	global_load_dwordx2 v[200:201], v[190:191], off offset:256 nt
	s_nop 0
	global_load_dwordx2 v[190:191], v[190:191], off offset:288 nt
	s_nop 0
	global_load_dwordx2 v[202:203], v[198:199], off nt
	global_load_dwordx2 v[204:205], v[198:199], off offset:32 nt
	global_load_dwordx2 v[206:207], v[198:199], off offset:256 nt
	s_nop 0
	global_load_dwordx2 v[198:199], v[198:199], off offset:288 nt
	v_lshlrev_b64 v[194:195], 13, v[160:161]
	v_lshl_add_u64 v[194:195], s[6:7], 0, v[194:195]
	v_lshlrev_b64 v[178:179], 13, v[178:179]
	v_lshl_add_u64 v[194:195], v[194:195], 0, v[156:157]
	v_lshl_add_u64 v[178:179], s[6:7], 0, v[178:179]
	v_lshl_add_u64 v[178:179], v[178:179], 0, v[156:157]
	s_and_b64 vcc, exec, s[0:1]
	s_mov_b64 s[0:1], -1
	s_waitcnt vmcnt(0)
	v_lshlrev_b32_e32 v208, 16, v170
	v_and_b32_e32 v209, 0xffff0000, v170
	v_lshlrev_b32_e32 v170, 16, v171
	v_and_b32_e32 v171, 0xffff0000, v171
	v_lshlrev_b32_e32 v210, 16, v172
	v_and_b32_e32 v211, 0xffff0000, v172
	v_lshlrev_b32_e32 v172, 16, v173
	v_and_b32_e32 v173, 0xffff0000, v173
	v_lshlrev_b32_e32 v214, 16, v176
	v_and_b32_e32 v215, 0xffff0000, v176
	v_lshlrev_b32_e32 v176, 16, v177
	v_and_b32_e32 v177, 0xffff0000, v177
	v_lshlrev_b32_e32 v212, 16, v174
	v_and_b32_e32 v213, 0xffff0000, v174
	v_lshlrev_b32_e32 v174, 16, v175
	v_and_b32_e32 v175, 0xffff0000, v175
	v_pk_fma_f32 v[126:127], v[126:127], v[142:143], v[170:171]
	v_pk_fma_f32 v[124:125], v[124:125], v[140:141], v[208:209]
	v_pk_fma_f32 v[122:123], v[122:123], v[138:139], v[172:173]
	v_pk_fma_f32 v[110:111], v[110:111], v[130:131], v[176:177]
	v_pk_fma_f32 v[108:109], v[108:109], v[128:129], v[214:215]
	v_lshlrev_b32_e32 v170, 16, v180
	v_and_b32_e32 v171, 0xffff0000, v180
	v_lshlrev_b32_e32 v172, 16, v181
	v_and_b32_e32 v173, 0xffff0000, v181
	v_pk_fma_f32 v[120:121], v[120:121], v[136:137], v[210:211]
	v_pk_fma_f32 v[114:115], v[114:115], v[134:135], v[174:175]
	v_pk_fma_f32 v[112:113], v[112:113], v[132:133], v[212:213]
	flat_store_dwordx4 v[194:195], v[124:127] sc1
	flat_store_dwordx4 v[194:195], v[120:123] offset:64 sc1
	flat_store_dwordx4 v[194:195], v[112:115] offset:512 sc1
	flat_store_dwordx4 v[194:195], v[108:111] offset:576 sc1
	v_lshlrev_b32_e32 v174, 16, v182
	v_and_b32_e32 v175, 0xffff0000, v182
	v_pk_fma_f32 v[110:111], v[118:119], v[142:143], v[172:173]
	v_pk_fma_f32 v[108:109], v[116:117], v[140:141], v[170:171]
	flat_store_dwordx4 v[178:179], v[108:111] sc1
	v_pk_fma_f32 v[104:105], v[104:105], v[136:137], v[174:175]
	s_nop 0
	v_lshlrev_b32_e32 v108, 16, v183
	v_and_b32_e32 v109, 0xffff0000, v183
	v_pk_fma_f32 v[106:107], v[106:107], v[138:139], v[108:109]
	flat_store_dwordx4 v[178:179], v[104:107] offset:64 sc1
	s_nop 1
	v_lshlrev_b32_e32 v104, 16, v184
	v_and_b32_e32 v105, 0xffff0000, v184
	v_lshlrev_b32_e32 v106, 16, v185
	v_and_b32_e32 v107, 0xffff0000, v185
	v_pk_fma_f32 v[102:103], v[102:103], v[134:135], v[106:107]
	v_pk_fma_f32 v[100:101], v[100:101], v[132:133], v[104:105]
	flat_store_dwordx4 v[178:179], v[100:103] offset:512 sc1
	s_nop 1
	v_lshlrev_b32_e32 v100, 16, v186
	v_and_b32_e32 v101, 0xffff0000, v186
	v_lshlrev_b32_e32 v102, 16, v187
	v_and_b32_e32 v103, 0xffff0000, v187
	v_pk_fma_f32 v[94:95], v[94:95], v[130:131], v[102:103]
	v_pk_fma_f32 v[92:93], v[92:93], v[128:129], v[100:101]
	flat_store_dwordx4 v[178:179], v[92:95] offset:576 sc1
	s_nop 1
	v_lshlrev_b32_e32 v92, 16, v192
	v_and_b32_e32 v93, 0xffff0000, v192
	v_pk_fma_f32 v[92:93], v[96:97], v[140:141], v[92:93]
	v_lshlrev_b64 v[96:97], 13, v[188:189]
	v_lshlrev_b32_e32 v94, 16, v193
	v_and_b32_e32 v95, 0xffff0000, v193
	v_lshl_add_u64 v[96:97], s[6:7], 0, v[96:97]
	v_pk_fma_f32 v[94:95], v[98:99], v[142:143], v[94:95]
	v_lshl_add_u64 v[96:97], v[96:97], 0, v[156:157]
	flat_store_dwordx4 v[96:97], v[92:95] sc1
	v_add_u32_e32 v98, 0xb0, v160
	v_ashrrev_i32_e32 v99, 31, v98
	v_lshlrev_b32_e32 v92, 16, v196
	v_and_b32_e32 v93, 0xffff0000, v196
	v_lshlrev_b32_e32 v94, 16, v197
	v_and_b32_e32 v95, 0xffff0000, v197
	v_pk_fma_f32 v[90:91], v[90:91], v[138:139], v[94:95]
	v_pk_fma_f32 v[88:89], v[88:89], v[136:137], v[92:93]
	flat_store_dwordx4 v[96:97], v[88:91] offset:64 sc1
	s_nop 1
	v_lshlrev_b32_e32 v88, 16, v200
	v_and_b32_e32 v89, 0xffff0000, v200
	v_lshlrev_b32_e32 v90, 16, v201
	v_and_b32_e32 v91, 0xffff0000, v201
	v_pk_fma_f32 v[86:87], v[86:87], v[134:135], v[90:91]
	v_pk_fma_f32 v[84:85], v[84:85], v[132:133], v[88:89]
	flat_store_dwordx4 v[96:97], v[84:87] offset:512 sc1
	v_add_u32_e32 v88, 0xa0, v160
	v_ashrrev_i32_e32 v89, 31, v88
	v_lshlrev_b32_e32 v84, 16, v190
	v_and_b32_e32 v85, 0xffff0000, v190
	v_lshlrev_b32_e32 v86, 16, v191
	v_and_b32_e32 v87, 0xffff0000, v191
	v_pk_fma_f32 v[78:79], v[78:79], v[130:131], v[86:87]
	v_pk_fma_f32 v[76:77], v[76:77], v[128:129], v[84:85]
	flat_store_dwordx4 v[96:97], v[76:79] offset:576 sc1
	s_nop 1
	v_lshlrev_b32_e32 v76, 16, v202
	v_and_b32_e32 v77, 0xffff0000, v202
	v_pk_fma_f32 v[76:77], v[80:81], v[140:141], v[76:77]
	v_lshlrev_b64 v[80:81], 13, v[162:163]
	v_lshlrev_b32_e32 v78, 16, v203
	v_and_b32_e32 v79, 0xffff0000, v203
	v_lshl_add_u64 v[80:81], s[6:7], 0, v[80:81]
	v_pk_fma_f32 v[78:79], v[82:83], v[142:143], v[78:79]
	v_lshl_add_u64 v[80:81], v[80:81], 0, v[156:157]
	flat_store_dwordx4 v[80:81], v[76:79] sc1
	s_nop 1
	v_lshlrev_b32_e32 v76, 16, v204
	v_and_b32_e32 v77, 0xffff0000, v204
	v_lshlrev_b32_e32 v78, 16, v205
	v_and_b32_e32 v79, 0xffff0000, v205
	v_pk_fma_f32 v[74:75], v[74:75], v[138:139], v[78:79]
	v_pk_fma_f32 v[72:73], v[72:73], v[136:137], v[76:77]
	flat_store_dwordx4 v[80:81], v[72:75] offset:64 sc1
	v_add_u32_e32 v78, 0x90, v160
	v_ashrrev_i32_e32 v79, 31, v78
	v_lshlrev_b32_e32 v72, 16, v206
	v_and_b32_e32 v73, 0xffff0000, v206
	v_lshlrev_b32_e32 v74, 16, v207
	v_and_b32_e32 v75, 0xffff0000, v207
	v_pk_fma_f32 v[70:71], v[70:71], v[134:135], v[74:75]
	v_pk_fma_f32 v[68:69], v[68:69], v[132:133], v[72:73]
	flat_store_dwordx4 v[80:81], v[68:71] offset:512 sc1
	s_nop 1
	v_lshlrev_b32_e32 v68, 16, v198
	v_and_b32_e32 v69, 0xffff0000, v198
	v_lshlrev_b32_e32 v70, 16, v199
	v_and_b32_e32 v71, 0xffff0000, v199
	v_pk_fma_f32 v[64:65], v[64:65], v[128:129], v[68:69]
	v_add_u32_e32 v68, 0x80, v160
	v_pk_fma_f32 v[66:67], v[66:67], v[130:131], v[70:71]
	v_ashrrev_i32_e32 v69, 31, v68
	flat_store_dwordx4 v[80:81], v[64:67] offset:576 sc1
	s_nop 1
	v_lshlrev_b64 v[64:65], 12, v[68:69]
	v_lshl_add_u64 v[64:65], v[158:159], 0, v[64:65]
	global_load_dwordx2 v[70:71], v[64:65], off nt
	global_load_dwordx2 v[72:73], v[64:65], off offset:32 nt
	global_load_dwordx2 v[74:75], v[64:65], off offset:256 nt
	global_load_dwordx2 v[76:77], v[64:65], off offset:288 nt
	v_lshlrev_b64 v[64:65], 12, v[78:79]
	v_lshl_add_u64 v[64:65], v[158:159], 0, v[64:65]
	global_load_dwordx2 v[80:81], v[64:65], off nt
	global_load_dwordx2 v[82:83], v[64:65], off offset:32 nt
	global_load_dwordx2 v[84:85], v[64:65], off offset:256 nt
	global_load_dwordx2 v[86:87], v[64:65], off offset:288 nt
	v_lshlrev_b64 v[64:65], 12, v[88:89]
	v_lshl_add_u64 v[64:65], v[158:159], 0, v[64:65]
	global_load_dwordx2 v[90:91], v[64:65], off nt
	global_load_dwordx2 v[92:93], v[64:65], off offset:32 nt
	global_load_dwordx2 v[94:95], v[64:65], off offset:256 nt
	global_load_dwordx2 v[96:97], v[64:65], off offset:288 nt
	v_lshlrev_b64 v[64:65], 12, v[98:99]
	v_lshl_add_u64 v[64:65], v[158:159], 0, v[64:65]
	global_load_dwordx2 v[100:101], v[64:65], off nt
	global_load_dwordx2 v[102:103], v[64:65], off offset:32 nt
	global_load_dwordx2 v[66:67], v[64:65], off offset:256 nt
	s_nop 0
	global_load_dwordx2 v[64:65], v[64:65], off offset:288 nt
	v_lshlrev_b64 v[68:69], 13, v[68:69]
	v_lshl_add_u64 v[68:69], s[6:7], 0, v[68:69]
	v_lshl_add_u64 v[68:69], v[68:69], 0, v[156:157]
	s_waitcnt vmcnt(0)
	v_lshlrev_b32_e32 v104, 16, v70
	v_and_b32_e32 v105, 0xffff0000, v70
	v_lshlrev_b32_e32 v70, 16, v71
	v_and_b32_e32 v71, 0xffff0000, v71
	v_pk_fma_f32 v[62:63], v[62:63], v[142:143], v[70:71]
	v_pk_fma_f32 v[60:61], v[60:61], v[140:141], v[104:105]
	flat_store_dwordx4 v[68:69], v[60:63] sc1
	s_nop 1
	v_lshlrev_b32_e32 v60, 16, v72
	v_and_b32_e32 v61, 0xffff0000, v72
	v_lshlrev_b32_e32 v62, 16, v73
	v_and_b32_e32 v63, 0xffff0000, v73
	v_pk_fma_f32 v[58:59], v[58:59], v[138:139], v[62:63]
	v_pk_fma_f32 v[56:57], v[56:57], v[136:137], v[60:61]
	flat_store_dwordx4 v[68:69], v[56:59] offset:64 sc1
	s_nop 1
	v_lshlrev_b32_e32 v56, 16, v74
	v_and_b32_e32 v57, 0xffff0000, v74
	v_lshlrev_b32_e32 v58, 16, v75
	v_and_b32_e32 v59, 0xffff0000, v75
	v_pk_fma_f32 v[54:55], v[54:55], v[134:135], v[58:59]
	v_pk_fma_f32 v[52:53], v[52:53], v[132:133], v[56:57]
	flat_store_dwordx4 v[68:69], v[52:55] offset:512 sc1
	s_nop 1
	v_lshlrev_b32_e32 v52, 16, v76
	v_and_b32_e32 v53, 0xffff0000, v76
	v_lshlrev_b32_e32 v54, 16, v77
	v_and_b32_e32 v55, 0xffff0000, v77
	v_pk_fma_f32 v[46:47], v[46:47], v[130:131], v[54:55]
	v_pk_fma_f32 v[44:45], v[44:45], v[128:129], v[52:53]
	flat_store_dwordx4 v[68:69], v[44:47] offset:576 sc1
	s_nop 1
	v_lshlrev_b32_e32 v44, 16, v80
	v_and_b32_e32 v45, 0xffff0000, v80
	v_pk_fma_f32 v[44:45], v[48:49], v[140:141], v[44:45]
	v_lshlrev_b64 v[48:49], 13, v[78:79]
	v_lshlrev_b32_e32 v46, 16, v81
	v_and_b32_e32 v47, 0xffff0000, v81
	v_lshl_add_u64 v[48:49], s[6:7], 0, v[48:49]
	v_pk_fma_f32 v[46:47], v[50:51], v[142:143], v[46:47]
	v_lshl_add_u64 v[48:49], v[48:49], 0, v[156:157]
	flat_store_dwordx4 v[48:49], v[44:47] sc1
	s_nop 1
	v_lshlrev_b32_e32 v44, 16, v82
	v_and_b32_e32 v45, 0xffff0000, v82
	v_lshlrev_b32_e32 v46, 16, v83
	v_and_b32_e32 v47, 0xffff0000, v83
	v_pk_fma_f32 v[42:43], v[42:43], v[138:139], v[46:47]
	v_pk_fma_f32 v[40:41], v[40:41], v[136:137], v[44:45]
	flat_store_dwordx4 v[48:49], v[40:43] offset:64 sc1
	s_nop 1
	v_lshlrev_b32_e32 v40, 16, v84
	v_and_b32_e32 v41, 0xffff0000, v84
	v_lshlrev_b32_e32 v42, 16, v85
	v_and_b32_e32 v43, 0xffff0000, v85
	v_pk_fma_f32 v[38:39], v[38:39], v[134:135], v[42:43]
	v_pk_fma_f32 v[36:37], v[36:37], v[132:133], v[40:41]
	flat_store_dwordx4 v[48:49], v[36:39] offset:512 sc1
	s_nop 1
	v_lshlrev_b32_e32 v36, 16, v86
	v_and_b32_e32 v37, 0xffff0000, v86
	v_lshlrev_b32_e32 v38, 16, v87
	v_and_b32_e32 v39, 0xffff0000, v87
	v_pk_fma_f32 v[30:31], v[30:31], v[130:131], v[38:39]
	v_pk_fma_f32 v[28:29], v[28:29], v[128:129], v[36:37]
	flat_store_dwordx4 v[48:49], v[28:31] offset:576 sc1
	s_nop 1
	v_lshlrev_b32_e32 v28, 16, v90
	v_and_b32_e32 v29, 0xffff0000, v90
	v_pk_fma_f32 v[28:29], v[32:33], v[140:141], v[28:29]
	v_lshlrev_b64 v[32:33], 13, v[88:89]
	v_lshlrev_b32_e32 v30, 16, v91
	v_and_b32_e32 v31, 0xffff0000, v91
	v_lshl_add_u64 v[32:33], s[6:7], 0, v[32:33]
	v_pk_fma_f32 v[30:31], v[34:35], v[142:143], v[30:31]
	v_lshl_add_u64 v[32:33], v[32:33], 0, v[156:157]
	flat_store_dwordx4 v[32:33], v[28:31] sc1
	s_nop 1
	v_lshlrev_b32_e32 v28, 16, v92
	v_and_b32_e32 v29, 0xffff0000, v92
	v_lshlrev_b32_e32 v30, 16, v93
	v_and_b32_e32 v31, 0xffff0000, v93
	v_pk_fma_f32 v[26:27], v[26:27], v[138:139], v[30:31]
	v_pk_fma_f32 v[24:25], v[24:25], v[136:137], v[28:29]
	flat_store_dwordx4 v[32:33], v[24:27] offset:64 sc1
	s_nop 1
	v_lshlrev_b32_e32 v24, 16, v94
	v_and_b32_e32 v25, 0xffff0000, v94
	v_lshlrev_b32_e32 v26, 16, v95
	v_and_b32_e32 v27, 0xffff0000, v95
	v_pk_fma_f32 v[22:23], v[22:23], v[134:135], v[26:27]
	v_pk_fma_f32 v[20:21], v[20:21], v[132:133], v[24:25]
	flat_store_dwordx4 v[32:33], v[20:23] offset:512 sc1
	s_nop 1
	v_lshlrev_b32_e32 v20, 16, v96
	v_and_b32_e32 v21, 0xffff0000, v96
	v_lshlrev_b32_e32 v22, 16, v97
	v_and_b32_e32 v23, 0xffff0000, v97
	v_pk_fma_f32 v[14:15], v[14:15], v[130:131], v[22:23]
	v_pk_fma_f32 v[12:13], v[12:13], v[128:129], v[20:21]
	flat_store_dwordx4 v[32:33], v[12:15] offset:576 sc1
	s_nop 1
	v_lshlrev_b32_e32 v12, 16, v100
	v_and_b32_e32 v13, 0xffff0000, v100
	v_pk_fma_f32 v[12:13], v[16:17], v[140:141], v[12:13]
	v_lshlrev_b64 v[16:17], 13, v[98:99]
	v_lshlrev_b32_e32 v14, 16, v101
	v_and_b32_e32 v15, 0xffff0000, v101
	v_lshl_add_u64 v[16:17], s[6:7], 0, v[16:17]
	v_pk_fma_f32 v[14:15], v[18:19], v[142:143], v[14:15]
	v_lshl_add_u64 v[16:17], v[16:17], 0, v[156:157]
	flat_store_dwordx4 v[16:17], v[12:15] sc1
	s_nop 1
	v_lshlrev_b32_e32 v12, 16, v102
	v_and_b32_e32 v13, 0xffff0000, v102
	v_lshlrev_b32_e32 v14, 16, v103
	v_and_b32_e32 v15, 0xffff0000, v103
	v_pk_fma_f32 v[10:11], v[10:11], v[138:139], v[14:15]
	v_pk_fma_f32 v[8:9], v[8:9], v[136:137], v[12:13]
	flat_store_dwordx4 v[16:17], v[8:11] offset:64 sc1
	s_nop 1
	v_lshlrev_b32_e32 v8, 16, v66
	v_and_b32_e32 v9, 0xffff0000, v66
	v_lshlrev_b32_e32 v10, 16, v67
	v_and_b32_e32 v11, 0xffff0000, v67
	v_pk_fma_f32 v[6:7], v[6:7], v[134:135], v[10:11]
	v_pk_fma_f32 v[4:5], v[4:5], v[132:133], v[8:9]
	flat_store_dwordx4 v[16:17], v[4:7] offset:512 sc1
	s_nop 1
	v_lshlrev_b32_e32 v4, 16, v64
	v_and_b32_e32 v5, 0xffff0000, v64
	v_lshlrev_b32_e32 v6, 16, v65
	v_and_b32_e32 v7, 0xffff0000, v65
	v_pk_fma_f32 v[2:3], v[2:3], v[130:131], v[6:7]
	v_pk_fma_f32 v[0:1], v[0:1], v[128:129], v[4:5]
	flat_store_dwordx4 v[16:17], v[0:3] offset:576 sc1
	s_cbranch_vccnz .LBB0_1077
	s_andn2_b64 vcc, exec, s[12:13]
	s_cbranch_vccnz .LBB0_1076
	s_barrier
	s_branch .LBB0_1076
